# NA and GQA: bias LUT is built once per workgroup and layer; the second unit of the same head reuses it from LDS
# baseline (speedup 1.0000x reference)
; template <int MODE, bool FROZEN = false>
; __device__ __forceinline__ bool attn_unit(LAS unsigned char* lds, const Params& p, int l, int ua, int ub) {
;     ...
;         const int h = ua, R0 = ub * 4; myrow = R0 + (wid >> 1); qtok0 = myrow * 64 + (wid & 1) * 32;
;         qcol = h * 64; kcol = 512 + h * 64; vcol = h * 64; ocol = h * 64;
;         const int rs_first = min(max(R0 - 4, 0), 248), rs_last = min(max(R0 + 3 - 4, 0), 248), my_rs = min(max(myrow - 4, 0), 248);
;         kt0 = rs_first * 64; NT = rs_last + 8 - rs_first; wt_lo = my_rs - rs_first; wt_hi = wt_lo + 8;
;         for (int i = tid; i < 15 * 127; i += 512) { const int dr_ = i / 127, dc_ = min(max(i % 127 - 48, 0), 30); lut[i] = p.na_rpb[(size_t)(l * 8 + h) * 465 + dr_ * 31 + dc_] * LOG2E; }
.LBB0_180:
	v_mov_b32_e32 v0, v228
	s_movk_i32 s0, 0x771
	s_and_b32 s8, s14, 7
	s_nop 0
	v_readfirstlane_b32 s15, v0
	v_cmp_gt_i32_e32 vcc, s0, v0
	s_and_saveexec_b64 s[0:1], vcc
	s_cbranch_execz .LBB0_188
	s_and_b32 s101, s30, 7
	s_cmp_eq_u32 s101, 0
	s_cselect_b32 s101, 1, 0
	s_cmp_lg_u32 s14, s33
	s_cselect_b32 s100, s101, 0
	s_cmp_lg_u32 s100, 0
	s_cbranch_scc1 .LBB0_188
	v_readlane_b32 s4, v255, 13
	s_or_b32 s4, s8, s4
	v_readlane_b32 s40, v254, 57
	v_max_i32_e32 v1, 0x571, v0
	s_mul_hi_i32 s5, s4, 0x744
	s_mulk_i32 s4, 0x744
	v_readlane_b32 s46, v254, 63
	v_sub_u32_e32 v1, v1, v0
	v_readlane_b32 s47, v255, 0
	s_add_u32 s4, s46, s4
	v_add_u32_e32 v1, 0x1ff, v1
	s_movk_i32 s10, 0x1ff
	s_addc_u32 s5, s47, s5
	v_cmp_lt_u32_e32 vcc, s10, v1
	s_mov_b64 s[12:13], -1
	v_mov_b32_e32 v2, v0
	v_readlane_b32 s41, v254, 58
	v_readlane_b32 s42, v254, 59
	v_readlane_b32 s43, v254, 60
	v_readlane_b32 s44, v254, 61
	v_readlane_b32 s45, v254, 62
	v_readlane_b32 s48, v255, 1
	v_readlane_b32 s49, v255, 2
	v_readlane_b32 s50, v255, 3
	v_readlane_b32 s51, v255, 4
	v_readlane_b32 s52, v255, 5
	v_readlane_b32 s53, v255, 6
	v_readlane_b32 s54, v255, 7
	v_readlane_b32 s55, v255, 8
	s_and_saveexec_b64 s[10:11], vcc
	s_cbranch_execz .LBB0_185
	v_lshrrev_b32_e32 v1, 9, v1
	v_add_u32_e32 v4, 1, v1
	v_and_b32_e32 v5, 0xfffffe, v4
	v_add_u32_e32 v1, 0x200, v0
	v_readlane_b32 s12, v254, 48
	v_mov_b32_e32 v7, v5
	v_mov_b64_e32 v[2:3], v[0:1]
	v_lshl_add_u32 v6, v0, 2, s12
	s_mov_b64 s[12:13], 0
	s_movk_i32 s16, 0x7f
	s_mov_b32 s17, 0x81020409
	s_mov_b32 s18, 0x3fb8aa3b

; template <int MODE, bool FROZEN = false>
; __device__ __forceinline__ bool attn_unit(LAS unsigned char* lds, const Params& p, int l, int ua, int ub) {
;     ...
;         const int g = ua, qb = ub, hq = g * 4 + (wid >> 1); qtok0 = qb * 64 + (wid & 1) * 32; lut_sel = wid >> 1;
;         qcol = 3072 + hq * 64; kcol = 3584 + g * 64; vcol = 1024 + g * 64; ocol = hq * 64;
;         const int tlo = max(qb - 2, 0), thi = min(qb + 2, S / 64 - 1); kt0 = tlo * 64; NT = thi - tlo + 1; wt_hi = NT;
;         for (int i = tid; i < 4 * 449; i += 512) { const int hh = i / 449, rel = i % 449 - 224; lut[i] = (rel >= -128 && rel <= 128) ? p.rel_bias[t5_bucket(rel) * 12 + 4 + g * 4 + hh] * LOG2E : NEGBIG; }
.LBB0_490:
	s_and_b32 s22, s20, 1
	v_mov_b32_e32 v2, v228
	s_movk_i32 s0, 0x704
	s_lshl_b32 s8, s22, 2
	v_readfirstlane_b32 s21, v2
	v_cmp_gt_i32_e32 vcc, s0, v2
	s_and_saveexec_b64 s[0:1], vcc
	s_cbranch_execz .LBB0_503
	s_and_b32 s101, s30, 7
	s_cmp_eq_u32 s101, 0
	s_cselect_b32 s101, 1, 0
	s_cmp_lg_u32 s20, s33
	s_cselect_b32 s100, s101, 0
	s_cmp_lg_u32 s100, 0
	s_cbranch_scc1 .LBB0_503
	v_readlane_b32 s4, v254, 48
	v_mov_b32_e32 v4, v2
	s_nop 0
	v_lshl_add_u32 v3, v2, 2, s4
	s_mov_b64 s[4:5], 0
	s_branch .LBB0_497
